# attention unit epilogues (all three modes): v_permlane32_swap pairs + global_store_dwordx4 instead of dwordx2 store ladders (half the store instructions, same bytes); pop wait adjusted to vmcnt(4)
# speedup vs baseline: 1.0061x; 1.0043x over previous
; __global__ void __launch_bounds__(NTHR, 2) mega_fwd(KArgs a) {
;     ...
;             for (;;) {
;                 if (threadIdx.x == 0) MISC[16] = atomicAdd(qhead, 1u);
;                 __syncthreads();
;                 const int u = (int)MISC[16];
.LBB0_912:
	s_mov_b64 s[0:1], exec
	v_readlane_b32 s4, v253, 4
	v_readlane_b32 s5, v253, 5
	s_and_b64 s[4:5], s[0:1], s[4:5]
	s_mov_b64 exec, s[4:5]
	s_cbranch_execz .LBB0_914
	v_readlane_b32 s4, v254, 10
	s_nop 1
	v_mov_b32_e32 v2, s4
	s_waitcnt vmcnt(4)
	ds_write_b32 v2, v249

; #define GAS __attribute__((address_space(1)))
; __device__ __forceinline__ float swapsum(float m) { auto rr = __builtin_amdgcn_permlane32_swap(__float_as_uint(m), __float_as_uint(m), false, false); return __uint_as_float(rr[0]) + __uint_as_float(rr[1]); }
; __device__ __forceinline__ unsigned cvtpk(float lo, float hi) { f32x2_t v = {lo, hi}; bf16x2_t b = __builtin_convertvector(v, bf16x2_t); return __builtin_bit_cast(unsigned, b); }
; template <int MODE> __device__ __forceinline__ void attn_unit4(LAS unsigned char* lds, const int uidx, const AttnArgs& A) {
;     ...
;     float lt = swapsum(lsum);
;     if (MODE == 2) lt += __builtin_amdgcn_exp2f(A.sinks[2 * hx + st] * LOG2E - mref);
;     const float inv = 1.0f / lt;
; #pragma unroll
;     for (int d = 0; d < NDB; ++d)
; #pragma unroll
;         for (int r = 0; r < 16; ++r) o[d][r] *= inv;
;     ...
;         GAS bf16_t* op = (GAS bf16_t*)A.O + orow * DM + (MODE == 1 ? 768 : 512) + (2 * hx + st) * 64 + 4 * hi;
; #pragma unroll
;         for (int d = 0; d < NDB; ++d)
; #pragma unroll
;             for (int g4 = 0; g4 < 4; ++g4) {
;                 u32x2 w; w.x = cvtpk(o[d][4 * g4], o[d][4 * g4 + 1]); w.y = cvtpk(o[d][4 * g4 + 2], o[d][4 * g4 + 3]);
;                 *(GAS u32x2*)(op + d * 32 + 8 * g4) = w;
;             }
.Lpf_m2:
	s_mov_b64 exec, s[76:77]
	v_mov_b32_e32 v131, v1
	s_setprio 0
	s_mul_i32 s5, s26, 0x5000
	s_add_i32 s5, s5, 0
	v_add_u32_e32 v0, s5, v141
	ds_read_b64_tr_b16 v[34:35], v0 offset:51200
	ds_read_b64_tr_b16 v[36:37], v0 offset:53760
	v_add_u32_e32 v38, 0xc800, v0
	s_ashr_i32 s5, s4, 31
	s_lshl_b64 s[4:5], s[4:5], 2
	s_add_u32 s4, s68, s4
	ds_read_b64_tr_b16 v[244:245], v0 offset:56320
	ds_read_b64_tr_b16 v[246:247], v0 offset:58880
	s_addc_u32 s5, s89, s5
	s_waitcnt lgkmcnt(2)
	v_mfma_f32_32x32x16_bf16 v[2:17], v[34:37], v[102:105], v[2:17]
	ds_read_b64_tr_b16 v[34:35], v0 offset:61440
	ds_read_b64_tr_b16 v[36:37], v0 offset:64000
	s_waitcnt lgkmcnt(2)
	v_mfma_f32_32x32x16_bf16 v[2:17], v[244:247], v[98:101], v[2:17]
	ds_read_b64_tr_b16 v[244:245], v38 offset:15360
	ds_read_b64_tr_b16 v[246:247], v38 offset:17920
	s_waitcnt lgkmcnt(2)
	v_mfma_f32_32x32x16_bf16 v[2:17], v[34:37], v[110:113], v[2:17]
	ds_read_b64_tr_b16 v[34:35], v0 offset:51264
	ds_read_b64_tr_b16 v[36:37], v0 offset:53824
	s_waitcnt lgkmcnt(2)
	v_mfma_f32_32x32x16_bf16 v[2:17], v[244:247], v[106:109], v[2:17]
	ds_read_b64_tr_b16 v[244:245], v0 offset:56384
	ds_read_b64_tr_b16 v[246:247], v0 offset:58944
	s_waitcnt lgkmcnt(2)
	v_mfma_f32_32x32x16_bf16 v[18:33], v[34:37], v[102:105], v[18:33]
	ds_read_b64_tr_b16 v[34:35], v0 offset:61504
	ds_read_b64_tr_b16 v[36:37], v0 offset:64064
	v_mov_b32_e32 v0, v160
	s_nop 1
	v_permlane32_swap_b32_e32 v160, v0
	v_add_f32_e32 v0, v160, v0
	s_waitcnt lgkmcnt(2)
	v_mfma_f32_32x32x16_bf16 v[18:33], v[244:247], v[98:101], v[18:33]
	ds_read_b64_tr_b16 v[244:245], v38 offset:15424
	ds_read_b64_tr_b16 v[246:247], v38 offset:17984
	s_waitcnt lgkmcnt(2)
	v_mfma_f32_32x32x16_bf16 v[18:33], v[34:37], v[110:113], v[18:33]
	s_waitcnt lgkmcnt(0)
	s_barrier
	v_mfma_f32_32x32x16_bf16 v[18:33], v[244:247], v[106:109], v[18:33]
	global_load_dword v34, v1, s[4:5]
	s_mov_b32 s4, 0x3fb8aa3b
	s_waitcnt vmcnt(0)
	v_fma_f32 v34, v34, s4, -v143
	v_exp_f32_e32 v34, v34
	s_nop 0
	v_add_f32_e32 v0, v0, v34
	v_div_scale_f32 v34, s[4:5], v0, v0, 1.0
	v_rcp_f32_e32 v35, v34
	s_nop 0
	v_fma_f32 v36, -v34, v35, 1.0
	v_fmac_f32_e32 v35, v36, v35
	v_div_scale_f32 v36, vcc, 1.0, v0, 1.0
	v_mul_f32_e32 v37, v36, v35
	v_fma_f32 v38, -v34, v37, v36
	v_fmac_f32_e32 v37, v38, v35
	v_fma_f32 v34, -v34, v37, v36
	v_div_fmas_f32 v34, v34, v35, v37
	v_div_fixup_f32 v0, v34, v0, 1.0
	v_pk_mul_f32 v[34:35], v[14:15], v[0:1] op_sel_hi:[1,0]
	v_pk_mul_f32 v[14:15], v[18:19], v[0:1] op_sel_hi:[1,0]
	v_lshlrev_b64 v[18:19], 11, v[130:131]
	v_lshl_add_u64 v[18:19], s[10:11], 0, v[18:19]
	v_pk_mul_f32 v[46:47], v[2:3], v[0:1] op_sel_hi:[1,0]
	v_pk_mul_f32 v[48:49], v[4:5], v[0:1] op_sel_hi:[1,0]
	v_pk_mul_f32 v[42:43], v[6:7], v[0:1] op_sel_hi:[1,0]
	v_pk_mul_f32 v[44:45], v[8:9], v[0:1] op_sel_hi:[1,0]
	v_pk_mul_f32 v[38:39], v[10:11], v[0:1] op_sel_hi:[1,0]
	v_pk_mul_f32 v[40:41], v[12:13], v[0:1] op_sel_hi:[1,0]
	v_pk_mul_f32 v[36:37], v[16:17], v[0:1] op_sel_hi:[1,0]
	v_pk_mul_f32 v[16:17], v[20:21], v[0:1] op_sel_hi:[1,0]
	v_pk_mul_f32 v[10:11], v[22:23], v[0:1] op_sel_hi:[1,0]
	v_pk_mul_f32 v[12:13], v[24:25], v[0:1] op_sel_hi:[1,0]
	v_pk_mul_f32 v[6:7], v[26:27], v[0:1] op_sel_hi:[1,0]
	v_pk_mul_f32 v[8:9], v[28:29], v[0:1] op_sel_hi:[1,0]
	v_pk_mul_f32 v[2:3], v[30:31], v[0:1] op_sel_hi:[1,0]
	v_pk_mul_f32 v[4:5], v[32:33], v[0:1] op_sel_hi:[1,0]
	v_lshl_add_u64 v[18:19], s[0:1], 1, v[18:19]
	v_lshlrev_b32_e32 v0, 1, v133
	v_lshl_add_u64 v[18:19], v[18:19], 0, v[0:1]
	v_lshlrev_b32_e32 v236, 1, v133
	v_mov_b32_e32 v237, 0
	v_lshl_add_u64 v[236:237], v[18:19], 0, v[236:237]
	v_cvt_pk_bf16_f32 v220, v46, v47
	v_cvt_pk_bf16_f32 v221, v48, v49
	v_cvt_pk_bf16_f32 v222, v42, v43
	v_cvt_pk_bf16_f32 v223, v44, v45
	s_nop 1
	v_permlane32_swap_b32_e32 v220, v222
	v_permlane32_swap_b32_e32 v221, v223
	global_store_dwordx4 v[236:237], v[220:223], off offset:1024
	v_cvt_pk_bf16_f32 v224, v38, v39
	v_cvt_pk_bf16_f32 v225, v40, v41
	v_cvt_pk_bf16_f32 v226, v34, v35
	v_cvt_pk_bf16_f32 v227, v36, v37
	s_nop 1
	v_permlane32_swap_b32_e32 v224, v226
	v_permlane32_swap_b32_e32 v225, v227
	global_store_dwordx4 v[236:237], v[224:227], off offset:1056
	v_cvt_pk_bf16_f32 v228, v14, v15
	v_cvt_pk_bf16_f32 v229, v16, v17
	v_cvt_pk_bf16_f32 v230, v10, v11
	v_cvt_pk_bf16_f32 v231, v12, v13
	s_nop 1
	v_permlane32_swap_b32_e32 v228, v230
	v_permlane32_swap_b32_e32 v229, v231
	global_store_dwordx4 v[236:237], v[228:231], off offset:1088
	v_cvt_pk_bf16_f32 v232, v6, v7
	v_cvt_pk_bf16_f32 v233, v8, v9
	v_cvt_pk_bf16_f32 v234, v2, v3
	v_cvt_pk_bf16_f32 v235, v4, v5
	s_nop 1
	v_permlane32_swap_b32_e32 v232, v234
	v_permlane32_swap_b32_e32 v233, v235
	global_store_dwordx4 v[236:237], v[232:235], off offset:1120
	s_barrier
	s_mov_b64 s[0:1], 0

; template <int MODE> __device__ __forceinline__ void attn_unit4(LAS unsigned char* lds, const int uidx, const AttnArgs& A) {
;     ...
;         if (st == 0) {
;             const float sx = wave_sum(A.dl[lane] * A.dl[64 + lane], lane), sy = wave_sum(A.dl[128 + lane] * A.dl[192 + lane], lane);
;             const float lam = __expf(sx) - __expf(sy) + A.lam_init;
;             float ss = 0.f;
; #pragma unroll
;             for (int d = 0; d < NDB; ++d)
; #pragma unroll
;                 for (int r = 0; r < 16; ++r) { const float v = o[d][r] - lam * X[(qg * 64 + d * 16 + r) * 64 + lane]; o[d][r] = v; ss += v * v; }
.LBB0_1005:
	s_cmpk_gt_u32 s30, 0xff
	s_waitcnt lgkmcnt(0)
	s_barrier
	s_cbranch_scc1 .LBB0_908
	v_lshlrev_b32_e32 v0, 2, v177
	s_lshl_b32 s0, s30, 8
	v_add_u32_e32 v0, 0, v0
	s_and_b32 s1, s0, 0xc000
	s_or_b32 s0, s0, 0x3f00
	v_mov_b32_e32 v14, v251
	v_add_u32_e32 v4, s1, v0
	v_add_u32_e32 v0, s0, v0
	ds_read2st64_b32 v[132:133], v4 offset1:1
	ds_read2st64_b32 v[134:135], v4 offset0:2 offset1:3
	ds_read2st64_b32 v[128:129], v4 offset0:4 offset1:5
	ds_read2st64_b32 v[130:131], v4 offset0:6 offset1:7
	ds_read2st64_b32 v[124:125], v4 offset0:8 offset1:9
	ds_read2st64_b32 v[126:127], v4 offset0:10 offset1:11
	ds_read2st64_b32 v[120:121], v4 offset0:12 offset1:13
	ds_read2st64_b32 v[122:123], v4 offset0:14 offset1:15
	ds_read2st64_b32 v[116:117], v4 offset0:16 offset1:17
	ds_read2st64_b32 v[118:119], v4 offset0:18 offset1:19
	ds_read2st64_b32 v[112:113], v4 offset0:20 offset1:21
	ds_read2st64_b32 v[114:115], v4 offset0:22 offset1:23
	ds_read2st64_b32 v[108:109], v4 offset0:24 offset1:25
	ds_read2st64_b32 v[110:111], v4 offset0:26 offset1:27
	ds_read2st64_b32 v[104:105], v4 offset0:28 offset1:29
	ds_read2st64_b32 v[106:107], v4 offset0:30 offset1:31
	ds_read2st64_b32 v[100:101], v4 offset0:32 offset1:33
	ds_read2st64_b32 v[102:103], v4 offset0:34 offset1:35
	ds_read2st64_b32 v[96:97], v4 offset0:36 offset1:37
	ds_read2st64_b32 v[98:99], v4 offset0:38 offset1:39
	ds_read2st64_b32 v[92:93], v4 offset0:40 offset1:41
	ds_read2st64_b32 v[94:95], v4 offset0:42 offset1:43
	ds_read2st64_b32 v[56:57], v4 offset0:44 offset1:45
	ds_read2st64_b32 v[58:59], v4 offset0:46 offset1:47
	ds_read2st64_b32 v[50:51], v4 offset0:48 offset1:49
	ds_read2st64_b32 v[52:53], v4 offset0:50 offset1:51
	ds_read2st64_b32 v[44:45], v4 offset0:52 offset1:53
	ds_read2st64_b32 v[46:47], v4 offset0:54 offset1:55
	ds_read2st64_b32 v[32:33], v4 offset0:56 offset1:57
	ds_read2st64_b32 v[42:43], v4 offset0:58 offset1:59
	ds_read2st64_b32 v[16:17], v4 offset0:60 offset1:61
	ds_read_b32 v4, v4 offset:15872
	ds_read_b32 v5, v0
	v_lshlrev_b32_e32 v0, 1, v181
	s_mov_b32 s0, 0xf800000
	s_waitcnt lgkmcnt(0)
	v_pk_fma_f32 v[8:9], v[14:15], v[4:5], v[2:3] op_sel_hi:[0,1,1] neg_lo:[1,0,0] neg_hi:[1,0,0]
	v_lshlrev_b64 v[2:3], 11, v[166:167]
	v_lshl_add_u64 v[2:3], s[10:11], 0, v[2:3]
	v_lshlrev_b32_e32 v15, 2, v181
	v_lshl_add_u64 v[2:3], s[26:27], 1, v[2:3]
	v_pk_fma_f32 v[88:89], v[132:133], v[14:15], v[88:89] op_sel_hi:[1,0,1] neg_lo:[1,0,0] neg_hi:[1,0,0]
	v_lshl_add_u64 v[6:7], v[2:3], 0, v[0:1]
	v_mul_f32_e32 v0, v89, v89
	v_pk_fma_f32 v[90:91], v[134:135], v[14:15], v[90:91] op_sel_hi:[1,0,1] neg_lo:[1,0,0] neg_hi:[1,0,0]
	v_pk_fma_f32 v[132:133], v[88:89], v[88:89], v[0:1] op_sel_hi:[1,1,0]
	v_mul_f32_e32 v0, v91, v91
	v_pk_fma_f32 v[132:133], v[90:91], v[90:91], v[132:133]
	v_pk_fma_f32 v[84:85], v[128:129], v[14:15], v[84:85] op_sel_hi:[1,0,1] neg_lo:[1,0,0] neg_hi:[1,0,0]
	v_pk_add_f32 v[132:133], v[0:1], v[132:133] op_sel_hi:[0,1]
	v_pk_fma_f32 v[128:129], v[84:85], v[84:85], v[132:133]
	v_mul_f32_e32 v0, v85, v85
	v_pk_fma_f32 v[86:87], v[14:15], v[130:131], v[86:87] op_sel_hi:[0,1,1] neg_lo:[1,0,0] neg_hi:[1,0,0]
	v_pk_add_f32 v[128:129], v[0:1], v[128:129] op_sel_hi:[0,1]
	v_pk_fma_f32 v[128:129], v[86:87], v[86:87], v[128:129]
	v_mul_f32_e32 v0, v87, v87
	v_pk_add_f32 v[128:129], v[0:1], v[128:129] op_sel_hi:[0,1]
	v_pk_fma_f32 v[80:81], v[14:15], v[124:125], v[80:81] op_sel_hi:[0,1,1] neg_lo:[1,0,0] neg_hi:[1,0,0]
	v_pk_fma_f32 v[124:125], v[80:81], v[80:81], v[128:129]
	v_mul_f32_e32 v0, v81, v81
	v_pk_fma_f32 v[82:83], v[14:15], v[126:127], v[82:83] op_sel_hi:[0,1,1] neg_lo:[1,0,0] neg_hi:[1,0,0]
	v_pk_add_f32 v[124:125], v[0:1], v[124:125] op_sel_hi:[0,1]
	v_pk_fma_f32 v[124:125], v[82:83], v[82:83], v[124:125]
	v_mul_f32_e32 v0, v83, v83
	v_pk_add_f32 v[124:125], v[0:1], v[124:125] op_sel_hi:[0,1]
	v_pk_fma_f32 v[76:77], v[14:15], v[120:121], v[76:77] op_sel_hi:[0,1,1] neg_lo:[1,0,0] neg_hi:[1,0,0]
	v_pk_fma_f32 v[120:121], v[76:77], v[76:77], v[124:125]
	v_mul_f32_e32 v0, v77, v77
	v_pk_fma_f32 v[78:79], v[14:15], v[122:123], v[78:79] op_sel_hi:[0,1,1] neg_lo:[1,0,0] neg_hi:[1,0,0]
	v_pk_add_f32 v[120:121], v[0:1], v[120:121] op_sel_hi:[0,1]
	v_pk_fma_f32 v[120:121], v[78:79], v[78:79], v[120:121]
	v_mul_f32_e32 v0, v79, v79
	v_pk_add_f32 v[120:121], v[0:1], v[120:121] op_sel_hi:[0,1]
	v_pk_fma_f32 v[72:73], v[14:15], v[116:117], v[72:73] op_sel_hi:[0,1,1] neg_lo:[1,0,0] neg_hi:[1,0,0]
	v_pk_fma_f32 v[116:117], v[72:73], v[72:73], v[120:121]
	v_mul_f32_e32 v0, v73, v73
	v_pk_fma_f32 v[74:75], v[14:15], v[118:119], v[74:75] op_sel_hi:[0,1,1] neg_lo:[1,0,0] neg_hi:[1,0,0]
	v_pk_add_f32 v[116:117], v[0:1], v[116:117] op_sel_hi:[0,1]
	v_pk_fma_f32 v[116:117], v[74:75], v[74:75], v[116:117]
	v_mul_f32_e32 v0, v75, v75
	v_pk_add_f32 v[116:117], v[0:1], v[116:117] op_sel_hi:[0,1]
	v_pk_fma_f32 v[68:69], v[14:15], v[112:113], v[68:69] op_sel_hi:[0,1,1] neg_lo:[1,0,0] neg_hi:[1,0,0]
	v_pk_fma_f32 v[112:113], v[68:69], v[68:69], v[116:117]
	v_mul_f32_e32 v0, v69, v69
	v_pk_fma_f32 v[70:71], v[14:15], v[114:115], v[70:71] op_sel_hi:[0,1,1] neg_lo:[1,0,0] neg_hi:[1,0,0]
	v_pk_add_f32 v[112:113], v[0:1], v[112:113] op_sel_hi:[0,1]
	v_pk_fma_f32 v[112:113], v[70:71], v[70:71], v[112:113]
	v_mul_f32_e32 v0, v71, v71
	v_pk_add_f32 v[112:113], v[0:1], v[112:113] op_sel_hi:[0,1]
	v_pk_fma_f32 v[64:65], v[14:15], v[108:109], v[64:65] op_sel_hi:[0,1,1] neg_lo:[1,0,0] neg_hi:[1,0,0]
	v_pk_fma_f32 v[108:109], v[64:65], v[64:65], v[112:113]
	v_mul_f32_e32 v0, v65, v65
	v_pk_fma_f32 v[66:67], v[14:15], v[110:111], v[66:67] op_sel_hi:[0,1,1] neg_lo:[1,0,0] neg_hi:[1,0,0]
; #define GAS __attribute__((address_space(1)))
; __device__ __forceinline__ float swapsum(float m) { auto rr = __builtin_amdgcn_permlane32_swap(__float_as_uint(m), __float_as_uint(m), false, false); return __uint_as_float(rr[0]) + __uint_as_float(rr[1]); }
; template <int MODE> __device__ __forceinline__ void attn_unit4(LAS unsigned char* lds, const int uidx, const AttnArgs& A) {
;     ...
;                 for (int r = 0; r < 16; ++r) { const float v = o[d][r] - lam * X[(qg * 64 + d * 16 + r) * 64 + lane]; o[d][r] = v; ss += v * v; }
;             ss = swapsum(ss);
;             const float rs = (1.0f / sqrtf(ss * (1.0f / 128.0f) + EPSN)) * (1.0f - A.lam_init);
;             GAS bf16_t* op = (GAS bf16_t*)A.O + orow * DM + hx * 128 + 4 * hi;
	v_pk_add_f32 v[108:109], v[0:1], v[108:109] op_sel_hi:[0,1]
	v_pk_fma_f32 v[108:109], v[66:67], v[66:67], v[108:109]
	v_mul_f32_e32 v0, v67, v67
	v_pk_add_f32 v[108:109], v[0:1], v[108:109] op_sel_hi:[0,1]
	v_pk_fma_f32 v[60:61], v[14:15], v[104:105], v[60:61] op_sel_hi:[0,1,1] neg_lo:[1,0,0] neg_hi:[1,0,0]
	v_pk_fma_f32 v[104:105], v[60:61], v[60:61], v[108:109]
	v_mul_f32_e32 v0, v61, v61
	v_pk_fma_f32 v[62:63], v[14:15], v[106:107], v[62:63] op_sel_hi:[0,1,1] neg_lo:[1,0,0] neg_hi:[1,0,0]
	v_pk_add_f32 v[104:105], v[0:1], v[104:105] op_sel_hi:[0,1]
	v_pk_fma_f32 v[104:105], v[62:63], v[62:63], v[104:105]
	v_mul_f32_e32 v0, v63, v63
	v_pk_add_f32 v[104:105], v[0:1], v[104:105] op_sel_hi:[0,1]
	v_pk_fma_f32 v[48:49], v[14:15], v[100:101], v[48:49] op_sel_hi:[0,1,1] neg_lo:[1,0,0] neg_hi:[1,0,0]
	v_pk_fma_f32 v[100:101], v[48:49], v[48:49], v[104:105]
	v_mul_f32_e32 v0, v49, v49
	v_pk_fma_f32 v[54:55], v[14:15], v[102:103], v[54:55] op_sel_hi:[0,1,1] neg_lo:[1,0,0] neg_hi:[1,0,0]
	v_pk_add_f32 v[100:101], v[0:1], v[100:101] op_sel_hi:[0,1]
	v_pk_fma_f32 v[100:101], v[54:55], v[54:55], v[100:101]
	v_mul_f32_e32 v0, v55, v55
	v_pk_add_f32 v[100:101], v[0:1], v[100:101] op_sel_hi:[0,1]
	v_pk_fma_f32 v[38:39], v[14:15], v[96:97], v[38:39] op_sel_hi:[0,1,1] neg_lo:[1,0,0] neg_hi:[1,0,0]
	v_pk_fma_f32 v[96:97], v[38:39], v[38:39], v[100:101]
	v_mul_f32_e32 v0, v39, v39
	v_pk_fma_f32 v[40:41], v[14:15], v[98:99], v[40:41] op_sel_hi:[0,1,1] neg_lo:[1,0,0] neg_hi:[1,0,0]
	v_pk_add_f32 v[96:97], v[0:1], v[96:97] op_sel_hi:[0,1]
	v_pk_fma_f32 v[96:97], v[40:41], v[40:41], v[96:97]
	v_mul_f32_e32 v0, v41, v41
	v_pk_add_f32 v[96:97], v[0:1], v[96:97] op_sel_hi:[0,1]
	v_pk_fma_f32 v[34:35], v[14:15], v[92:93], v[34:35] op_sel_hi:[0,1,1] neg_lo:[1,0,0] neg_hi:[1,0,0]
	v_pk_fma_f32 v[92:93], v[34:35], v[34:35], v[96:97]
	v_mul_f32_e32 v0, v35, v35
	v_pk_fma_f32 v[36:37], v[14:15], v[94:95], v[36:37] op_sel_hi:[0,1,1] neg_lo:[1,0,0] neg_hi:[1,0,0]
	v_pk_add_f32 v[92:93], v[0:1], v[92:93] op_sel_hi:[0,1]
	v_pk_fma_f32 v[92:93], v[36:37], v[36:37], v[92:93]
	v_mul_f32_e32 v0, v37, v37
	v_pk_add_f32 v[92:93], v[0:1], v[92:93] op_sel_hi:[0,1]
	v_pk_fma_f32 v[56:57], v[14:15], v[56:57], v[26:27] op_sel_hi:[0,1,1] neg_lo:[1,0,0] neg_hi:[1,0,0]
	v_pk_fma_f32 v[26:27], v[56:57], v[56:57], v[92:93]
	v_mul_f32_e32 v0, v57, v57
	v_pk_fma_f32 v[30:31], v[14:15], v[58:59], v[30:31] op_sel_hi:[0,1,1] neg_lo:[1,0,0] neg_hi:[1,0,0]
	v_pk_add_f32 v[26:27], v[0:1], v[26:27] op_sel_hi:[0,1]
	v_pk_fma_f32 v[26:27], v[30:31], v[30:31], v[26:27]
	v_mul_f32_e32 v0, v31, v31
	v_pk_add_f32 v[58:59], v[0:1], v[26:27] op_sel_hi:[0,1]
	v_pk_fma_f32 v[24:25], v[14:15], v[50:51], v[24:25] op_sel_hi:[0,1,1] neg_lo:[1,0,0] neg_hi:[1,0,0]
	v_pk_fma_f32 v[26:27], v[14:15], v[52:53], v[28:29] op_sel_hi:[0,1,1] neg_lo:[1,0,0] neg_hi:[1,0,0]
	v_pk_fma_f32 v[28:29], v[24:25], v[24:25], v[58:59]
	v_mul_f32_e32 v0, v25, v25
	v_pk_add_f32 v[28:29], v[0:1], v[28:29] op_sel_hi:[0,1]
	v_pk_fma_f32 v[28:29], v[26:27], v[26:27], v[28:29]
	v_mul_f32_e32 v0, v27, v27
	v_pk_add_f32 v[28:29], v[0:1], v[28:29] op_sel_hi:[0,1]
	v_pk_fma_f32 v[20:21], v[14:15], v[44:45], v[20:21] op_sel_hi:[0,1,1] neg_lo:[1,0,0] neg_hi:[1,0,0]
	v_pk_fma_f32 v[28:29], v[20:21], v[20:21], v[28:29]
	v_mul_f32_e32 v0, v21, v21
	v_pk_fma_f32 v[22:23], v[14:15], v[46:47], v[22:23] op_sel_hi:[0,1,1] neg_lo:[1,0,0] neg_hi:[1,0,0]
	v_pk_add_f32 v[28:29], v[0:1], v[28:29] op_sel_hi:[0,1]
	v_pk_fma_f32 v[28:29], v[22:23], v[22:23], v[28:29]
	v_mul_f32_e32 v0, v23, v23
	v_pk_add_f32 v[28:29], v[0:1], v[28:29] op_sel_hi:[0,1]
	v_pk_fma_f32 v[18:19], v[14:15], v[32:33], v[18:19] op_sel_hi:[0,1,1] neg_lo:[1,0,0] neg_hi:[1,0,0]
	v_pk_fma_f32 v[28:29], v[18:19], v[18:19], v[28:29]
	v_mul_f32_e32 v0, v19, v19
	v_pk_fma_f32 v[12:13], v[14:15], v[42:43], v[12:13] op_sel_hi:[0,1,1] neg_lo:[1,0,0] neg_hi:[1,0,0]
	v_pk_add_f32 v[28:29], v[0:1], v[28:29] op_sel_hi:[0,1]
	v_pk_fma_f32 v[28:29], v[12:13], v[12:13], v[28:29]
	v_mul_f32_e32 v0, v13, v13
	v_pk_add_f32 v[28:29], v[0:1], v[28:29] op_sel_hi:[0,1]
	v_pk_fma_f32 v[10:11], v[14:15], v[16:17], v[10:11] op_sel_hi:[0,1,1] neg_lo:[1,0,0] neg_hi:[1,0,0]
	v_pk_fma_f32 v[16:17], v[10:11], v[10:11], v[28:29]
	v_mul_f32_e32 v0, v11, v11
	v_pk_add_f32 v[16:17], v[0:1], v[16:17] op_sel_hi:[0,1]
	v_pk_fma_f32 v[16:17], v[8:9], v[8:9], v[16:17]
	v_mul_f32_e32 v0, v9, v9
	v_pk_add_f32 v[16:17], v[0:1], v[16:17] op_sel_hi:[0,1]
	v_mov_b32_e32 v0, v16
	s_nop 1
	v_permlane32_swap_b32_e32 v16, v0
	v_add_f32_e32 v0, v16, v0
	v_fmamk_f32 v0, v0, 0x3c000000, v218
	v_cmp_gt_f32_e32 vcc, s0, v0
	v_mul_f32_e32 v14, 0x4f800000, v0
	s_nop 0
	v_cndmask_b32_e32 v0, v0, v14, vcc
	v_sqrt_f32_e32 v14, v0
	s_nop 0
	v_add_u32_e32 v16, -1, v14
	v_fma_f32 v17, -v16, v14, v0
	v_cmp_ge_f32_e64 s[0:1], 0, v17
	v_add_u32_e32 v17, 1, v14
	s_nop 0
	v_cndmask_b32_e64 v16, v14, v16, s[0:1]
	v_fma_f32 v14, -v17, v14, v0
	v_cmp_lt_f32_e64 s[0:1], 0, v14
	s_nop 1
	v_cndmask_b32_e64 v14, v16, v17, s[0:1]
	v_mul_f32_e32 v16, 0x37800000, v14
	v_cndmask_b32_e32 v14, v14, v16, vcc
	v_mov_b32_e32 v16, 0x260
	v_cmp_class_f32_e32 vcc, v0, v16
	s_nop 1
	v_cndmask_b32_e32 v0, v14, v0, vcc
	v_div_scale_f32 v14, s[0:1], v0, v0, 1.0
	v_rcp_f32_e32 v16, v14
	s_nop 0
	v_fma_f32 v17, -v14, v16, 1.0
	v_fmac_f32_e32 v16, v17, v16
	v_div_scale_f32 v17, vcc, 1.0, v0, 1.0
	v_mul_f32_e32 v28, v17, v16
	v_fma_f32 v29, -v14, v28, v17
	v_fmac_f32_e32 v28, v29, v16
	v_fma_f32 v14, -v14, v28, v17
	v_div_fmas_f32 v14, v14, v16, v28
	v_div_fixup_f32 v0, v14, v0, 1.0
	v_mul_f32_e32 v0, v191, v0
	v_pk_mul_f32 v[16:17], v[88:89], v[0:1] op_sel_hi:[1,0]
	v_pk_mul_f32 v[12:13], v[12:13], v[0:1] op_sel_hi:[1,0]
	s_waitcnt vmcnt(0)
; #define GAS __attribute__((address_space(1)))
; __device__ __forceinline__ unsigned cvtpk(float lo, float hi) { f32x2_t v = {lo, hi}; bf16x2_t b = __builtin_convertvector(v, bf16x2_t); return __builtin_bit_cast(unsigned, b); }
; template <int MODE> __device__ __forceinline__ void attn_unit4(LAS unsigned char* lds, const int uidx, const AttnArgs& A) {
;     ...
;             GAS bf16_t* op = (GAS bf16_t*)A.O + orow * DM + hx * 128 + 4 * hi;
; #pragma unroll
;             for (int d = 0; d < NDB; ++d)
; #pragma unroll
;                 for (int g4 = 0; g4 < 4; ++g4) {
;                     const f32x4 gv = *(const GAS f32x4*)((const GAS float*)A.gsub + d * 32 + 8 * g4 + 4 * hi);
;                     u32x2 w; w.x = cvtpk(o[d][4 * g4] * rs * gv[0], o[d][4 * g4 + 1] * rs * gv[1]); w.y = cvtpk(o[d][4 * g4 + 2] * rs * gv[2], o[d][4 * g4 + 3] * rs * gv[3]);
;                     *(GAS u32x2*)(op + d * 32 + 8 * g4) = w;
;                 }
	v_lshlrev_b32_e32 v246, 1, v181
	v_mov_b32_e32 v247, 0
	v_lshl_add_u64 v[246:247], v[6:7], 0, v[246:247]
	v_pk_mul_f32 v[2:3], v[136:137], v[16:17]
	v_pk_mul_f32 v[16:17], v[90:91], v[0:1] op_sel_hi:[1,0]
	v_cvt_pk_bf16_f32 v236, v2, v3
	v_pk_mul_f32 v[4:5], v[138:139], v[16:17]
	v_pk_mul_f32 v[16:17], v[84:85], v[0:1] op_sel_hi:[1,0]
	v_cvt_pk_bf16_f32 v237, v4, v5
	v_pk_mul_f32 v[10:11], v[10:11], v[0:1] op_sel_hi:[1,0]
	v_pk_mul_f32 v[8:9], v[8:9], v[0:1] op_sel_hi:[1,0]
	v_pk_mul_f32 v[2:3], v[140:141], v[16:17]
	v_pk_mul_f32 v[16:17], v[86:87], v[0:1] op_sel_hi:[1,0]
	v_cvt_pk_bf16_f32 v238, v2, v3
	v_pk_mul_f32 v[4:5], v[142:143], v[16:17]
	v_pk_mul_f32 v[16:17], v[80:81], v[0:1] op_sel_hi:[1,0]
	v_cvt_pk_bf16_f32 v239, v4, v5
	s_nop 1
	v_permlane32_swap_b32_e32 v236, v238
	v_permlane32_swap_b32_e32 v237, v239
	global_store_dwordx4 v[246:247], v[236:239], off
	v_pk_mul_f32 v[2:3], v[144:145], v[16:17]
	v_pk_mul_f32 v[16:17], v[82:83], v[0:1] op_sel_hi:[1,0]
	v_cvt_pk_bf16_f32 v240, v2, v3
	v_pk_mul_f32 v[4:5], v[146:147], v[16:17]
	v_pk_mul_f32 v[16:17], v[76:77], v[0:1] op_sel_hi:[1,0]
	v_cvt_pk_bf16_f32 v241, v4, v5
	v_pk_mul_f32 v[2:3], v[148:149], v[16:17]
	v_pk_mul_f32 v[16:17], v[78:79], v[0:1] op_sel_hi:[1,0]
	v_cvt_pk_bf16_f32 v242, v2, v3
	v_pk_mul_f32 v[4:5], v[150:151], v[16:17]
	v_pk_mul_f32 v[16:17], v[72:73], v[0:1] op_sel_hi:[1,0]
	v_cvt_pk_bf16_f32 v243, v4, v5
	s_nop 1
	v_permlane32_swap_b32_e32 v240, v242
	v_permlane32_swap_b32_e32 v241, v243
	global_store_dwordx4 v[246:247], v[240:243], off offset:32
	v_pk_mul_f32 v[2:3], v[16:17], v[152:153]
	v_pk_mul_f32 v[16:17], v[74:75], v[0:1] op_sel_hi:[1,0]
	v_cvt_pk_bf16_f32 v236, v2, v3
	v_pk_mul_f32 v[4:5], v[16:17], v[154:155]
	v_pk_mul_f32 v[16:17], v[68:69], v[0:1] op_sel_hi:[1,0]
	v_cvt_pk_bf16_f32 v237, v4, v5
	v_pk_mul_f32 v[2:3], v[16:17], v[156:157]
	v_pk_mul_f32 v[16:17], v[70:71], v[0:1] op_sel_hi:[1,0]
	v_cvt_pk_bf16_f32 v238, v2, v3
	v_pk_mul_f32 v[4:5], v[16:17], v[158:159]
	v_pk_mul_f32 v[16:17], v[64:65], v[0:1] op_sel_hi:[1,0]
	v_cvt_pk_bf16_f32 v239, v4, v5
	s_nop 1
	v_permlane32_swap_b32_e32 v236, v238
	v_permlane32_swap_b32_e32 v237, v239
	global_store_dwordx4 v[246:247], v[236:239], off offset:64
	v_pk_mul_f32 v[2:3], v[16:17], v[160:161]
	v_pk_mul_f32 v[16:17], v[66:67], v[0:1] op_sel_hi:[1,0]
	v_cvt_pk_bf16_f32 v240, v2, v3
	v_pk_mul_f32 v[4:5], v[16:17], v[162:163]
	v_pk_mul_f32 v[16:17], v[60:61], v[0:1] op_sel_hi:[1,0]
	v_cvt_pk_bf16_f32 v241, v4, v5
	v_pk_mul_f32 v[2:3], v[16:17], v[192:193]
	v_pk_mul_f32 v[16:17], v[62:63], v[0:1] op_sel_hi:[1,0]
	v_cvt_pk_bf16_f32 v242, v2, v3
	v_pk_mul_f32 v[4:5], v[16:17], v[194:195]
	v_pk_mul_f32 v[16:17], v[48:49], v[0:1] op_sel_hi:[1,0]
	v_cvt_pk_bf16_f32 v243, v4, v5
	s_nop 1
	v_permlane32_swap_b32_e32 v240, v242
	v_permlane32_swap_b32_e32 v241, v243
	global_store_dwordx4 v[246:247], v[240:243], off offset:96
	v_pk_mul_f32 v[2:3], v[16:17], v[196:197]
	v_pk_mul_f32 v[16:17], v[54:55], v[0:1] op_sel_hi:[1,0]
	v_cvt_pk_bf16_f32 v236, v2, v3
	v_pk_mul_f32 v[4:5], v[16:17], v[198:199]
	v_pk_mul_f32 v[16:17], v[38:39], v[0:1] op_sel_hi:[1,0]
	v_cvt_pk_bf16_f32 v237, v4, v5
	v_pk_mul_f32 v[2:3], v[16:17], v[200:201]
	v_pk_mul_f32 v[16:17], v[40:41], v[0:1] op_sel_hi:[1,0]
	v_cvt_pk_bf16_f32 v238, v2, v3
	v_pk_mul_f32 v[4:5], v[16:17], v[202:203]
	v_pk_mul_f32 v[16:17], v[34:35], v[0:1] op_sel_hi:[1,0]
	v_cvt_pk_bf16_f32 v239, v4, v5
	s_nop 1
	v_permlane32_swap_b32_e32 v236, v238
	v_permlane32_swap_b32_e32 v237, v239
	global_store_dwordx4 v[246:247], v[236:239], off offset:128
	v_pk_mul_f32 v[2:3], v[16:17], v[204:205]
	v_pk_mul_f32 v[16:17], v[36:37], v[0:1] op_sel_hi:[1,0]
	v_cvt_pk_bf16_f32 v240, v2, v3
	v_pk_mul_f32 v[4:5], v[16:17], v[206:207]
	v_pk_mul_f32 v[16:17], v[56:57], v[0:1] op_sel_hi:[1,0]
	v_cvt_pk_bf16_f32 v241, v4, v5
	v_pk_mul_f32 v[2:3], v[16:17], v[208:209]
	v_pk_mul_f32 v[16:17], v[30:31], v[0:1] op_sel_hi:[1,0]
	v_cvt_pk_bf16_f32 v242, v2, v3
	v_pk_mul_f32 v[4:5], v[16:17], v[210:211]
	v_pk_mul_f32 v[16:17], v[24:25], v[0:1] op_sel_hi:[1,0]
	v_cvt_pk_bf16_f32 v243, v4, v5
	s_nop 1
	v_permlane32_swap_b32_e32 v240, v242
	v_permlane32_swap_b32_e32 v241, v243
	global_store_dwordx4 v[246:247], v[240:243], off offset:160
	v_pk_mul_f32 v[2:3], v[16:17], v[212:213]
	v_pk_mul_f32 v[16:17], v[26:27], v[0:1] op_sel_hi:[1,0]
	v_cvt_pk_bf16_f32 v236, v2, v3
	v_pk_mul_f32 v[4:5], v[16:17], v[214:215]
	v_pk_mul_f32 v[16:17], v[20:21], v[0:1] op_sel_hi:[1,0]
	v_cvt_pk_bf16_f32 v237, v4, v5
	v_pk_mul_f32 v[2:3], v[16:17], v[220:221]
	v_pk_mul_f32 v[16:17], v[22:23], v[0:1] op_sel_hi:[1,0]
	v_cvt_pk_bf16_f32 v238, v2, v3
	v_pk_mul_f32 v[4:5], v[16:17], v[222:223]
	v_pk_mul_f32 v[16:17], v[18:19], v[0:1] op_sel_hi:[1,0]
	v_cvt_pk_bf16_f32 v239, v4, v5
	s_nop 1
	v_permlane32_swap_b32_e32 v236, v238
	v_permlane32_swap_b32_e32 v237, v239
	global_store_dwordx4 v[246:247], v[236:239], off offset:192
	v_pk_mul_f32 v[2:3], v[16:17], v[228:229]
	v_pk_mul_f32 v[4:5], v[12:13], v[230:231]
	v_cvt_pk_bf16_f32 v240, v2, v3
	v_cvt_pk_bf16_f32 v241, v4, v5
	v_pk_mul_f32 v[2:3], v[10:11], v[232:233]
	v_pk_mul_f32 v[4:5], v[8:9], v[234:235]
	v_cvt_pk_bf16_f32 v242, v2, v3
	v_cvt_pk_bf16_f32 v243, v4, v5
	s_nop 1
	v_permlane32_swap_b32_e32 v240, v242
	v_permlane32_swap_b32_e32 v241, v243
	global_store_dwordx4 v[246:247], v[240:243], off offset:224
	s_branch .LBB0_908

; #define GAS __attribute__((address_space(1)))
; __device__ __forceinline__ float swapsum(float m) { auto rr = __builtin_amdgcn_permlane32_swap(__float_as_uint(m), __float_as_uint(m), false, false); return __uint_as_float(rr[0]) + __uint_as_float(rr[1]); }
; __device__ __forceinline__ unsigned cvtpk(float lo, float hi) { f32x2_t v = {lo, hi}; bf16x2_t b = __builtin_convertvector(v, bf16x2_t); return __builtin_bit_cast(unsigned, b); }
; template <int MODE> __device__ __forceinline__ void attn_unit4(LAS unsigned char* lds, const int uidx, const AttnArgs& A) {
;     ...
;     float lt = swapsum(lsum);
;     if (MODE == 2) lt += __builtin_amdgcn_exp2f(A.sinks[2 * hx + st] * LOG2E - mref);
;     const float inv = 1.0f / lt;
; #pragma unroll
;     for (int d = 0; d < NDB; ++d)
; #pragma unroll
;         for (int r = 0; r < 16; ++r) o[d][r] *= inv;
;     ...
;         GAS bf16_t* op = (GAS bf16_t*)A.O + orow * DM + (MODE == 1 ? 768 : 512) + (2 * hx + st) * 64 + 4 * hi;
; #pragma unroll
;         for (int d = 0; d < NDB; ++d)
; #pragma unroll
;             for (int g4 = 0; g4 < 4; ++g4) {
;                 u32x2 w; w.x = cvtpk(o[d][4 * g4], o[d][4 * g4 + 1]); w.y = cvtpk(o[d][4 * g4 + 2], o[d][4 * g4 + 3]);
;                 *(GAS u32x2*)(op + d * 32 + 8 * g4) = w;
;             }
.Lpf_m1:
	s_mov_b64 exec, s[76:77]
	v_fmac_f32_e32 v42, v143, v142
	s_setprio 0
	v_add_u32_e32 v43, 0x16800, v197
	ds_read_b64_tr_b16 v[44:45], v43
	ds_read_b64_tr_b16 v[46:47], v43 offset:2560
	ds_read_b64_tr_b16 v[244:245], v43 offset:5120
	ds_read_b64_tr_b16 v[246:247], v43 offset:7680
	s_waitcnt lgkmcnt(2)
	v_mfma_f32_32x32x16_bf16 v[18:33], v[44:47], v[50:53], v[18:33]
	ds_read_b64_tr_b16 v[44:45], v43 offset:10240
	ds_read_b64_tr_b16 v[46:47], v43 offset:12800
	s_waitcnt lgkmcnt(2)
	v_mfma_f32_32x32x16_bf16 v[18:33], v[244:247], v[54:57], v[18:33]
	ds_read_b64_tr_b16 v[244:245], v43 offset:15360
	ds_read_b64_tr_b16 v[246:247], v43 offset:17920
	s_waitcnt lgkmcnt(2)
	v_mfma_f32_32x32x16_bf16 v[18:33], v[44:47], v[34:37], v[18:33]
	ds_read_b64_tr_b16 v[44:45], v43 offset:64
	ds_read_b64_tr_b16 v[46:47], v43 offset:2624
	s_waitcnt lgkmcnt(2)
	v_mfma_f32_32x32x16_bf16 v[18:33], v[244:247], v[38:41], v[18:33]
	ds_read_b64_tr_b16 v[244:245], v43 offset:5184
	ds_read_b64_tr_b16 v[246:247], v43 offset:7744
	s_waitcnt lgkmcnt(2)
	v_mfma_f32_32x32x16_bf16 v[2:17], v[44:47], v[50:53], v[2:17]
	ds_read_b64_tr_b16 v[44:45], v43 offset:10304
	ds_read_b64_tr_b16 v[46:47], v43 offset:12864
	s_waitcnt lgkmcnt(2)
	v_mfma_f32_32x32x16_bf16 v[2:17], v[244:247], v[54:57], v[2:17]
	ds_read_b64_tr_b16 v[244:245], v43 offset:15424
	ds_read_b64_tr_b16 v[246:247], v43 offset:17984
	s_waitcnt lgkmcnt(2)
	v_mfma_f32_32x32x16_bf16 v[2:17], v[44:47], v[34:37], v[2:17]
	s_waitcnt lgkmcnt(0)
	s_barrier
	v_mfma_f32_32x32x16_bf16 v[2:17], v[244:247], v[38:41], v[2:17]
	v_mov_b32_e32 v34, v42
	s_nop 1
	v_permlane32_swap_b32_e32 v42, v34
	v_add_f32_e32 v34, v42, v34
	v_div_scale_f32 v35, s[0:1], v34, v34, 1.0
	v_rcp_f32_e32 v36, v35
	s_lshl_b32 s0, s6, 6
	s_ashr_i32 s1, s0, 31
	v_fma_f32 v37, -v35, v36, 1.0
	v_fmac_f32_e32 v36, v37, v36
	v_div_scale_f32 v37, vcc, 1.0, v34, 1.0
	v_mul_f32_e32 v38, v37, v36
	v_fma_f32 v39, -v35, v38, v37
	v_fmac_f32_e32 v38, v39, v36
	v_fma_f32 v35, -v35, v38, v37
	v_div_fmas_f32 v35, v35, v36, v38
	v_div_fixup_f32 v34, v35, v34, 1.0
	v_pk_mul_f32 v[18:19], v[18:19], v[34:35] op_sel_hi:[1,0]
	v_pk_mul_f32 v[20:21], v[20:21], v[34:35] op_sel_hi:[1,0]
	v_pk_mul_f32 v[22:23], v[22:23], v[34:35] op_sel_hi:[1,0]
	v_pk_mul_f32 v[24:25], v[24:25], v[34:35] op_sel_hi:[1,0]
	v_pk_mul_f32 v[26:27], v[26:27], v[34:35] op_sel_hi:[1,0]
	v_pk_mul_f32 v[28:29], v[28:29], v[34:35] op_sel_hi:[1,0]
	v_pk_mul_f32 v[30:31], v[30:31], v[34:35] op_sel_hi:[1,0]
	v_pk_mul_f32 v[32:33], v[32:33], v[34:35] op_sel_hi:[1,0]
	v_pk_mul_f32 v[2:3], v[2:3], v[34:35] op_sel_hi:[1,0]
	v_pk_mul_f32 v[4:5], v[4:5], v[34:35] op_sel_hi:[1,0]
	v_pk_mul_f32 v[6:7], v[6:7], v[34:35] op_sel_hi:[1,0]
	v_pk_mul_f32 v[8:9], v[8:9], v[34:35] op_sel_hi:[1,0]
	v_pk_mul_f32 v[10:11], v[10:11], v[34:35] op_sel_hi:[1,0]
	v_pk_mul_f32 v[12:13], v[12:13], v[34:35] op_sel_hi:[1,0]
	v_pk_mul_f32 v[14:15], v[14:15], v[34:35] op_sel_hi:[1,0]
	v_pk_mul_f32 v[16:17], v[16:17], v[34:35] op_sel_hi:[1,0]
	v_lshlrev_b64 v[34:35], 11, v[0:1]
	v_lshl_add_u64 v[34:35], s[10:11], 0, v[34:35]
	v_lshl_add_u64 v[34:35], s[0:1], 1, v[34:35]
	v_lshlrev_b32_e32 v0, 1, v196
	v_lshl_add_u64 v[34:35], v[34:35], 0, v[0:1]
	v_lshlrev_b32_e32 v236, 1, v196
	v_mov_b32_e32 v237, 0
	v_lshl_add_u64 v[236:237], v[34:35], 0, v[236:237]
	v_cvt_pk_bf16_f32 v220, v18, v19
	v_cvt_pk_bf16_f32 v221, v20, v21
	v_cvt_pk_bf16_f32 v222, v22, v23
	v_cvt_pk_bf16_f32 v223, v24, v25
	s_nop 1
	v_permlane32_swap_b32_e32 v220, v222
	v_permlane32_swap_b32_e32 v221, v223
	global_store_dwordx4 v[236:237], v[220:223], off offset:1536
	v_cvt_pk_bf16_f32 v224, v26, v27
	v_cvt_pk_bf16_f32 v225, v28, v29
	v_cvt_pk_bf16_f32 v226, v30, v31
	v_cvt_pk_bf16_f32 v227, v32, v33
	s_nop 1
	v_permlane32_swap_b32_e32 v224, v226
	v_permlane32_swap_b32_e32 v225, v227
	global_store_dwordx4 v[236:237], v[224:227], off offset:1568
	v_cvt_pk_bf16_f32 v228, v2, v3
	v_cvt_pk_bf16_f32 v229, v4, v5
	v_cvt_pk_bf16_f32 v230, v6, v7
	v_cvt_pk_bf16_f32 v231, v8, v9
	s_nop 1
	v_permlane32_swap_b32_e32 v228, v230
	v_permlane32_swap_b32_e32 v229, v231
	global_store_dwordx4 v[236:237], v[228:231], off offset:1600
	v_cvt_pk_bf16_f32 v232, v10, v11
	v_cvt_pk_bf16_f32 v233, v12, v13
	v_cvt_pk_bf16_f32 v234, v14, v15
	v_cvt_pk_bf16_f32 v235, v16, v17
	s_nop 1
	v_permlane32_swap_b32_e32 v232, v234
	v_permlane32_swap_b32_e32 v233, v235
	global_store_dwordx4 v[236:237], v[232:235], off offset:1632
	s_barrier
	s_cbranch_execnz .LBB0_909
	s_branch .LBB0_971
